# gate stores nt sc1 + final-output row stores nt sc1 + no entry grid.sync
# speedup vs baseline: 1.0156x; 1.0156x over previous
; __device__ __forceinline__ float wave_sum(float v) {
;     v += __int_as_float(__builtin_amdgcn_update_dpp(0, __float_as_int(v), 0xB1, 0xf, 0xf, true));
;     v += __int_as_float(__builtin_amdgcn_update_dpp(0, __float_as_int(v), 0x4E, 0xf, 0xf, true));
;     v += __int_as_float(__builtin_amdgcn_update_dpp(0, __float_as_int(v), 0x141, 0xf, 0xf, true));
;     v += __int_as_float(__builtin_amdgcn_update_dpp(0, __float_as_int(v), 0x140, 0xf, 0xf, true));
;     const int iv = __float_as_int(v);
;     const float r0 = __int_as_float(__builtin_amdgcn_readlane(iv, 0)), r1 = __int_as_float(__builtin_amdgcn_readlane(iv, 16)), r2 = __int_as_float(__builtin_amdgcn_readlane(iv, 32)), r3 = __int_as_float(__builtin_amdgcn_readlane(iv, 48));
;     return (r0 + r1) + (r2 + r3);
; }
; __device__ __forceinline__ void phase_rows(const Ctx& c, int l) {
;     ...
;     for (int m0 = gw; m0 < MTOK; m0 += 2 * NGW) {
;         f32x4 v[2][4];
; #pragma unroll
;         for (int q = 0; q < 2; ++q) { const int mr = min(m0 + q * NGW, MTOK - 1); const f32x4* xr = (const f32x4*)(src + (size_t)mr * DM) + lane;
; #pragma unroll
;             for (int j = 0; j < 4; ++j) v[q][j] = xr[64 * j]; }
; #pragma unroll
;         for (int q = 0; q < 2; ++q) {
;         const int m = m0 + q * NGW;
;         if (m >= MTOK) continue;
;         if (l > 0) {
;             float s = 0.f;
; #pragma unroll
;             for (int j = 0; j < 4; ++j) s += (v[q][j].x + v[q][j].y) + (v[q][j].z + v[q][j].w);
;             const float mean = wave_sum(s) * (1.f / DM); float s2 = 0.f;
; #pragma unroll
;             for (int j = 0; j < 4; ++j) { v[q][j] = v[q][j] - mean; s2 += (v[q][j].x * v[q][j].x + v[q][j].y * v[q][j].y) + (v[q][j].z * v[q][j].z + v[q][j].w * v[q][j].w); }
;             const float rstd = 1.f / sqrtf(wave_sum(s2) * (1.f / DM) + LN_EPS);
;             const f32x4* gp = (const f32x4*)(c.inp(IN_LNG) + (size_t)(l - 1) * DM) + lane; const f32x4* bp = (const f32x4*)(c.inp(IN_LNB) + (size_t)(l - 1) * DM) + lane;
;             f32x4* orow = (f32x4*)(c.out + (size_t)m * DM) + lane;
; #pragma unroll
;             for (int j = 0; j < 4; ++j) { v[q][j] = v[q][j] * rstd * gp[64 * j] + bp[64 * j]; if (l == NLAYER) orow[64 * j] = v[q][j]; }
;             if (l < NLAYER && lane == 0) *(float2*)((float*)(c.ws + WS_STATS) + (size_t)m * 2) = make_float2(mean, rstd);
.LBB0_487:
	s_add_i32 s54, s46, s26
	s_ashr_i32 s47, s46, 31
	s_min_i32 s16, s54, 0x7fff
	s_lshl_b64 s[60:61], s[46:47], 12
	s_ashr_i32 s17, s16, 31
	s_waitcnt vmcnt(0)
	v_lshl_add_u64 v[138:139], v[174:175], 0, s[60:61]
	s_lshl_b64 s[16:17], s[16:17], 12
	global_load_dwordx4 v[166:169], v[138:139], off
	global_load_dwordx4 v[162:165], v[138:139], off offset:1024
	global_load_dwordx4 v[158:161], v[138:139], off offset:2048
	global_load_dwordx4 v[154:157], v[138:139], off offset:3072
	v_lshl_add_u64 v[138:139], v[174:175], 0, s[16:17]
	global_load_dwordx4 v[150:153], v[138:139], off
	global_load_dwordx4 v[146:149], v[138:139], off offset:1024
	global_load_dwordx4 v[142:145], v[138:139], off offset:2048
	s_nop 0
	global_load_dwordx4 v[138:141], v[138:139], off offset:3072
	v_cndmask_b32_e64 v96, 0, 1, s[48:49]
	v_cmp_ne_u32_e64 s[42:43], 1, v96
	s_andn2_b64 vcc, exec, s[48:49]
	s_cbranch_vccnz .LBB0_500
	s_waitcnt vmcnt(0)
	v_mov_b32_e32 v170, v167
	v_mov_b32_e32 v171, v168
	v_mov_b32_e32 v172, v166
	v_mov_b32_e32 v173, v169
	v_pk_add_f32 v[170:171], v[170:171], v[172:173]
	v_mov_b32_e32 v172, v163
	v_mov_b32_e32 v173, v164
	v_mov_b32_e32 v180, v162
	v_mov_b32_e32 v181, v165
	v_pk_add_f32 v[172:173], v[172:173], v[180:181]
	v_add_f32_e32 v96, v170, v171
	v_pk_add_f32 v[172:173], v[172:173], v[172:173] op_sel:[0,1] op_sel_hi:[1,0]
	v_add_f32_e32 v170, 0, v96
	v_add_f32_e32 v180, v158, v159
	v_add_f32_e32 v182, v160, v161
	v_mov_b32_e32 v171, v154
	v_mov_b32_e32 v173, v155
	v_mov_b32_e32 v181, v156
	v_mov_b32_e32 v183, v157
	v_pk_add_f32 v[170:171], v[170:171], v[172:173]
	v_pk_add_f32 v[172:173], v[180:181], v[182:183]
	s_load_dwordx4 s[64:67], s[12:13], 0x98
	v_pk_add_f32 v[170:171], v[170:171], v[172:173]
	v_lshl_add_u64 v[184:185], v[178:179], 0, s[60:61]
	v_add_f32_e32 v96, v170, v171
	s_nop 1
	v_add_f32_dpp v96, v96, v96 quad_perm:[1,0,3,2] row_mask:0xf bank_mask:0xf bound_ctrl:1
	s_nop 1
	v_add_f32_dpp v96, v96, v96 quad_perm:[2,3,0,1] row_mask:0xf bank_mask:0xf bound_ctrl:1
	s_nop 1
	v_add_f32_dpp v96, v96, v96 row_half_mirror row_mask:0xf bank_mask:0xf bound_ctrl:1
	s_nop 1
	v_add_f32_dpp v96, v96, v96 row_mirror row_mask:0xf bank_mask:0xf bound_ctrl:1
	s_nop 0
	v_readlane_b32 s0, v96, 16
	v_readlane_b32 s6, v96, 48
	v_readlane_b32 s16, v96, 0
	v_readlane_b32 s17, v96, 32
	v_mov_b32_e32 v170, s0
	v_mov_b32_e32 v171, s6
	v_pk_add_f32 v[170:171], s[16:17], v[170:171]
	s_nop 0
	v_add_f32_e32 v96, v170, v171
	v_fmamk_f32 v167, v96, 0xba800000, v167
	v_fmamk_f32 v166, v96, 0xba800000, v166
	v_fmamk_f32 v169, v96, 0xba800000, v169
	v_fmac_f32_e32 v168, 0xba800000, v96
	v_pk_mul_f32 v[170:171], v[168:169], v[168:169]
	v_pk_mul_f32 v[172:173], v[166:167], v[166:167]
	v_fmamk_f32 v183, v96, 0xba800000, v165
	v_pk_mov_b32 v[180:181], v[172:173], v[170:171] op_sel:[1,0]
	v_mov_b32_e32 v173, v171
	v_fmamk_f32 v182, v96, 0xba800000, v164
	v_fmamk_f32 v163, v96, 0xba800000, v163
	v_fmac_f32_e32 v162, 0xba800000, v96
	v_pk_add_f32 v[170:171], v[180:181], v[172:173]
	v_pk_mul_f32 v[164:165], v[182:183], v[182:183]
	v_pk_mul_f32 v[172:173], v[162:163], v[162:163]
	v_fmac_f32_e32 v158, 0xba800000, v96
	v_pk_mov_b32 v[180:181], v[172:173], v[164:165] op_sel:[1,0]
	v_mov_b32_e32 v173, v165
	v_pk_add_f32 v[164:165], v[180:181], v[172:173]
	v_fmamk_f32 v160, v96, 0xba800000, v160
	v_pk_add_f32 v[164:165], v[164:165], v[164:165] op_sel_hi:[0,1]
	v_fmamk_f32 v159, v96, 0xba800000, v159
	v_mul_f32_e32 v164, v158, v158
	v_fmamk_f32 v161, v96, 0xba800000, v161
	v_pk_fma_f32 v[172:173], v[158:159], v[158:159], v[164:165] op_sel_hi:[1,1,0]
	v_mul_f32_e32 v164, v160, v160
	v_pk_add_f32 v[170:171], v[170:171], v[170:171] op_sel_hi:[0,1]
	v_pk_fma_f32 v[180:181], v[160:161], v[160:161], v[164:165] op_sel_hi:[1,1,0]
	v_fmamk_f32 v157, v96, 0xba800000, v157
	v_fmamk_f32 v156, v96, 0xba800000, v156
	v_fmamk_f32 v155, v96, 0xba800000, v155
	v_fmac_f32_e32 v154, 0xba800000, v96
	v_mul_f32_e32 v172, v154, v154
	v_mul_f32_e32 v180, v155, v155
	v_mul_f32_e32 v170, v156, v156
	v_mul_f32_e32 v164, v157, v157
	v_pk_add_f32 v[172:173], v[172:173], v[180:181]
	v_pk_add_f32 v[164:165], v[170:171], v[164:165]
	s_nop 0
	v_pk_add_f32 v[164:165], v[172:173], v[164:165]
	s_nop 0
	v_add_f32_e32 v164, v164, v165
	s_nop 1
	v_add_f32_dpp v164, v164, v164 quad_perm:[1,0,3,2] row_mask:0xf bank_mask:0xf bound_ctrl:1
	s_nop 1
	v_add_f32_dpp v164, v164, v164 quad_perm:[2,3,0,1] row_mask:0xf bank_mask:0xf bound_ctrl:1
	s_nop 1
	v_add_f32_dpp v164, v164, v164 row_half_mirror row_mask:0xf bank_mask:0xf bound_ctrl:1
	s_nop 1
	v_add_f32_dpp v164, v164, v164 row_mirror row_mask:0xf bank_mask:0xf bound_ctrl:1
	s_nop 0
	v_readlane_b32 s0, v164, 16
	v_readlane_b32 s6, v164, 48
	v_readlane_b32 s16, v164, 0
	v_readlane_b32 s17, v164, 32
	v_mov_b32_e32 v164, s0
	v_mov_b32_e32 v165, s6
	v_pk_add_f32 v[164:165], s[16:17], v[164:165]
	s_nop 0
	v_add_f32_e32 v164, v164, v165
	v_fmamk_f32 v164, v164, 0x3a800000, v219
	v_cmp_gt_f32_e32 vcc, s87, v164
	v_mul_f32_e32 v165, 0x4f800000, v164
	s_nop 0
	v_cndmask_b32_e32 v164, v164, v165, vcc
	v_sqrt_f32_e32 v165, v164
	s_nop 0
	v_add_u32_e32 v170, -1, v165
	v_fma_f32 v171, -v170, v165, v164
	v_cmp_ge_f32_e64 s[40:41], 0, v171
	v_add_u32_e32 v171, 1, v165
	s_nop 0
	v_cndmask_b32_e64 v170, v165, v170, s[40:41]
	v_fma_f32 v165, -v171, v165, v164
	v_cmp_lt_f32_e64 s[40:41], 0, v165
	s_nop 1
	v_cndmask_b32_e64 v165, v170, v171, s[40:41]
	v_mul_f32_e32 v170, 0x37800000, v165
	v_cndmask_b32_e32 v165, v165, v170, vcc
	v_cmp_class_f32_e32 vcc, v164, v213
	s_nop 1
	v_cndmask_b32_e32 v164, v165, v164, vcc
	v_div_scale_f32 v165, s[16:17], v164, v164, 1.0
	v_rcp_f32_e32 v170, v165
	s_lshl_b64 s[16:17], s[22:23], 2
	s_waitcnt lgkmcnt(0)
	s_add_u32 s20, s64, s16
	s_addc_u32 s21, s65, s17
	v_fma_f32 v171, -v165, v170, 1.0
	v_fmac_f32_e32 v170, v171, v170
	v_div_scale_f32 v171, vcc, 1.0, v164, 1.0
	v_mul_f32_e32 v172, v171, v170
	v_fma_f32 v173, -v165, v172, v171
	v_fmac_f32_e32 v172, v173, v170
	v_fma_f32 v165, -v165, v172, v171
	v_div_fmas_f32 v165, v165, v170, v172
	v_div_fixup_f32 v180, v165, v164, 1.0
	v_lshlrev_b64 v[164:165], 4, v[200:201]
	s_add_u32 s16, s66, s16
	v_lshl_add_u64 v[186:187], s[20:21], 0, v[164:165]
	s_addc_u32 s17, s67, s17
	v_lshl_add_u64 v[188:189], s[16:17], 0, v[164:165]
	v_pk_mul_f32 v[190:191], v[166:167], v[180:181] op_sel_hi:[1,0]
	global_load_dwordx4 v[164:167], v[186:187], off
	global_load_dwordx4 v[170:173], v[188:189], off
	v_pk_mul_f32 v[168:169], v[168:169], v[180:181] op_sel_hi:[1,0]
	s_andn2_b64 vcc, exec, s[50:51]
	s_waitcnt vmcnt(0)
	v_pk_fma_f32 v[168:169], v[166:167], v[168:169], v[172:173]
	v_pk_fma_f32 v[166:167], v[164:165], v[190:191], v[170:171]
	v_cndmask_b32_e64 v164, 0, 1, s[50:51]
	v_cmp_ne_u32_e64 s[40:41], 1, v164
	s_cbranch_vccnz .LBB0_490
	global_store_dwordx4 v[184:185], v[166:169], off nt sc1
; __device__ __forceinline__ void phase_rows(const Ctx& c, int l) {
;     ...
;             f32x4* orow = (f32x4*)(c.out + (size_t)m * DM) + lane;
; #pragma unroll
;             for (int j = 0; j < 4; ++j) { v[q][j] = v[q][j] * rstd * gp[64 * j] + bp[64 * j]; if (l == NLAYER) orow[64 * j] = v[q][j]; }
.LBB0_490:
	global_load_dwordx4 v[190:193], v[186:187], off offset:1024
	global_load_dwordx4 v[202:205], v[188:189], off offset:1024
	v_mov_b32_e32 v181, v180
	v_mov_b32_e32 v170, v180
	v_mov_b32_e32 v171, v180
	v_pk_mul_f32 v[164:165], v[182:183], v[170:171]
	v_pk_mul_f32 v[162:163], v[162:163], v[180:181]
	s_and_b64 vcc, exec, s[40:41]
	s_waitcnt vmcnt(0)
	v_pk_fma_f32 v[164:165], v[164:165], v[192:193], v[204:205]
	v_pk_fma_f32 v[162:163], v[162:163], v[190:191], v[202:203]
	s_cbranch_vccnz .LBB0_492
	global_store_dwordx4 v[184:185], v[162:165], off offset:1024 nt sc1
.LBB0_492:
	v_pk_mul_f32 v[182:183], v[160:161], v[170:171]
	v_pk_mul_f32 v[190:191], v[158:159], v[180:181]
	global_load_dwordx4 v[158:161], v[186:187], off offset:2048
	global_load_dwordx4 v[170:173], v[188:189], off offset:2048
	s_and_b64 vcc, exec, s[40:41]
	s_waitcnt vmcnt(0)
	v_pk_fma_f32 v[160:161], v[182:183], v[160:161], v[172:173]
	v_pk_fma_f32 v[158:159], v[190:191], v[158:159], v[170:171]
	s_cbranch_vccnz .LBB0_494
	global_store_dwordx4 v[184:185], v[158:161], off offset:2048 nt sc1
.LBB0_494:
	v_mov_b32_e32 v170, v180
	v_mov_b32_e32 v171, v180
	v_pk_mul_f32 v[182:183], v[156:157], v[170:171]
	v_pk_mul_f32 v[190:191], v[154:155], v[180:181]
	global_load_dwordx4 v[154:157], v[186:187], off offset:3072
	global_load_dwordx4 v[170:173], v[188:189], off offset:3072
	s_and_b64 vcc, exec, s[40:41]
	s_waitcnt vmcnt(0)
	v_pk_fma_f32 v[156:157], v[182:183], v[156:157], v[172:173]
	v_pk_fma_f32 v[154:155], v[190:191], v[154:155], v[170:171]
	s_cbranch_vccnz .LBB0_496
	global_store_dwordx4 v[184:185], v[154:157], off offset:3072 nt sc1

; __device__ __forceinline__ float wave_sum(float v) {
;     v += __int_as_float(__builtin_amdgcn_update_dpp(0, __float_as_int(v), 0xB1, 0xf, 0xf, true));
;     v += __int_as_float(__builtin_amdgcn_update_dpp(0, __float_as_int(v), 0x4E, 0xf, 0xf, true));
;     v += __int_as_float(__builtin_amdgcn_update_dpp(0, __float_as_int(v), 0x141, 0xf, 0xf, true));
;     v += __int_as_float(__builtin_amdgcn_update_dpp(0, __float_as_int(v), 0x140, 0xf, 0xf, true));
;     const int iv = __float_as_int(v);
;     const float r0 = __int_as_float(__builtin_amdgcn_readlane(iv, 0)), r1 = __int_as_float(__builtin_amdgcn_readlane(iv, 16)), r2 = __int_as_float(__builtin_amdgcn_readlane(iv, 32)), r3 = __int_as_float(__builtin_amdgcn_readlane(iv, 48));
;     return (r0 + r1) + (r2 + r3);
; }
; __device__ __forceinline__ void phase_rows(const Ctx& c, int l) {
;     ...
;         for (int q = 0; q < 2; ++q) {
;         const int m = m0 + q * NGW;
;         if (m >= MTOK) continue;
;         if (l > 0) {
;             float s = 0.f;
; #pragma unroll
;             for (int j = 0; j < 4; ++j) s += (v[q][j].x + v[q][j].y) + (v[q][j].z + v[q][j].w);
;             const float mean = wave_sum(s) * (1.f / DM); float s2 = 0.f;
; #pragma unroll
;             for (int j = 0; j < 4; ++j) { v[q][j] = v[q][j] - mean; s2 += (v[q][j].x * v[q][j].x + v[q][j].y * v[q][j].y) + (v[q][j].z * v[q][j].z + v[q][j].w * v[q][j].w); }
;             const float rstd = 1.f / sqrtf(wave_sum(s2) * (1.f / DM) + LN_EPS);
;             const f32x4* gp = (const f32x4*)(c.inp(IN_LNG) + (size_t)(l - 1) * DM) + lane; const f32x4* bp = (const f32x4*)(c.inp(IN_LNB) + (size_t)(l - 1) * DM) + lane;
;             f32x4* orow = (f32x4*)(c.out + (size_t)m * DM) + lane;
; #pragma unroll
;             for (int j = 0; j < 4; ++j) { v[q][j] = v[q][j] * rstd * gp[64 * j] + bp[64 * j]; if (l == NLAYER) orow[64 * j] = v[q][j]; }
;             if (l < NLAYER && lane == 0) *(float2*)((float*)(c.ws + WS_STATS) + (size_t)m * 2) = make_float2(mean, rstd);
.LBB0_504:
	s_and_b64 vcc, exec, s[42:43]
	s_cbranch_vccnz .LBB0_516
	s_waitcnt vmcnt(0)
	v_mov_b32_e32 v154, v151
	v_mov_b32_e32 v155, v152
	v_mov_b32_e32 v156, v150
	v_mov_b32_e32 v157, v153
	v_pk_add_f32 v[154:155], v[154:155], v[156:157]
	v_mov_b32_e32 v156, v147
	v_mov_b32_e32 v157, v148
	v_mov_b32_e32 v158, v146
	v_mov_b32_e32 v159, v149
	v_pk_add_f32 v[156:157], v[156:157], v[158:159]
	v_add_f32_e32 v96, v154, v155
	v_pk_add_f32 v[156:157], v[156:157], v[156:157] op_sel:[0,1] op_sel_hi:[1,0]
	v_add_f32_e32 v154, 0, v96
	v_add_f32_e32 v158, v142, v143
	v_add_f32_e32 v160, v144, v145
	v_mov_b32_e32 v155, v138
	v_mov_b32_e32 v157, v139
	v_mov_b32_e32 v159, v140
	v_mov_b32_e32 v161, v141
	v_pk_add_f32 v[154:155], v[154:155], v[156:157]
	v_pk_add_f32 v[156:157], v[158:159], v[160:161]
	s_load_dwordx4 s[60:63], s[12:13], 0x98
	v_pk_add_f32 v[154:155], v[154:155], v[156:157]
	s_nop 0
	v_add_f32_e32 v96, v154, v155
	s_nop 1
	v_add_f32_dpp v96, v96, v96 quad_perm:[1,0,3,2] row_mask:0xf bank_mask:0xf bound_ctrl:1
	s_nop 1
	v_add_f32_dpp v96, v96, v96 quad_perm:[2,3,0,1] row_mask:0xf bank_mask:0xf bound_ctrl:1
	s_nop 1
	v_add_f32_dpp v96, v96, v96 row_half_mirror row_mask:0xf bank_mask:0xf bound_ctrl:1
	s_nop 1
	v_add_f32_dpp v96, v96, v96 row_mirror row_mask:0xf bank_mask:0xf bound_ctrl:1
	s_nop 0
	v_readlane_b32 s0, v96, 16
	v_readlane_b32 s6, v96, 48
	v_readlane_b32 s16, v96, 0
	v_readlane_b32 s17, v96, 32
	v_mov_b32_e32 v154, s0
	v_mov_b32_e32 v155, s6
	v_pk_add_f32 v[154:155], s[16:17], v[154:155]
	s_nop 0
	v_add_f32_e32 v96, v154, v155
	v_fmamk_f32 v151, v96, 0xba800000, v151
	v_fmamk_f32 v150, v96, 0xba800000, v150
	v_fmamk_f32 v153, v96, 0xba800000, v153
	v_fmac_f32_e32 v152, 0xba800000, v96
	v_pk_mul_f32 v[154:155], v[152:153], v[152:153]
	v_pk_mul_f32 v[156:157], v[150:151], v[150:151]
	v_fmamk_f32 v161, v96, 0xba800000, v149
	v_pk_mov_b32 v[158:159], v[156:157], v[154:155] op_sel:[1,0]
	v_mov_b32_e32 v157, v155
	v_fmamk_f32 v160, v96, 0xba800000, v148
	v_fmamk_f32 v147, v96, 0xba800000, v147
	v_fmac_f32_e32 v146, 0xba800000, v96
	v_pk_add_f32 v[154:155], v[158:159], v[156:157]
	v_pk_mul_f32 v[148:149], v[160:161], v[160:161]
	v_pk_mul_f32 v[156:157], v[146:147], v[146:147]
	v_fmac_f32_e32 v142, 0xba800000, v96
	v_pk_mov_b32 v[158:159], v[156:157], v[148:149] op_sel:[1,0]
	v_mov_b32_e32 v157, v149
	v_pk_add_f32 v[148:149], v[158:159], v[156:157]
	v_fmamk_f32 v144, v96, 0xba800000, v144
	v_pk_add_f32 v[148:149], v[148:149], v[148:149] op_sel_hi:[0,1]
	v_fmamk_f32 v143, v96, 0xba800000, v143
	v_mul_f32_e32 v148, v142, v142
	v_fmamk_f32 v145, v96, 0xba800000, v145
	v_pk_fma_f32 v[156:157], v[142:143], v[142:143], v[148:149] op_sel_hi:[1,1,0]
	v_mul_f32_e32 v148, v144, v144
	v_pk_add_f32 v[154:155], v[154:155], v[154:155] op_sel_hi:[0,1]
	v_pk_fma_f32 v[158:159], v[144:145], v[144:145], v[148:149] op_sel_hi:[1,1,0]
	v_fmamk_f32 v141, v96, 0xba800000, v141
	v_fmamk_f32 v140, v96, 0xba800000, v140
	v_fmamk_f32 v139, v96, 0xba800000, v139
	v_fmac_f32_e32 v138, 0xba800000, v96
	v_mul_f32_e32 v156, v138, v138
	v_mul_f32_e32 v158, v139, v139
	v_mul_f32_e32 v154, v140, v140
	v_mul_f32_e32 v148, v141, v141
	v_pk_add_f32 v[156:157], v[156:157], v[158:159]
	v_pk_add_f32 v[148:149], v[154:155], v[148:149]
	s_nop 0
	v_pk_add_f32 v[148:149], v[156:157], v[148:149]
	s_nop 0
	v_add_f32_e32 v148, v148, v149
	s_nop 1
	v_add_f32_dpp v148, v148, v148 quad_perm:[1,0,3,2] row_mask:0xf bank_mask:0xf bound_ctrl:1
	s_nop 1
	v_add_f32_dpp v148, v148, v148 quad_perm:[2,3,0,1] row_mask:0xf bank_mask:0xf bound_ctrl:1
	s_nop 1
	v_add_f32_dpp v148, v148, v148 row_half_mirror row_mask:0xf bank_mask:0xf bound_ctrl:1
	s_nop 1
	v_add_f32_dpp v148, v148, v148 row_mirror row_mask:0xf bank_mask:0xf bound_ctrl:1
	s_nop 0
	v_readlane_b32 s0, v148, 16
	v_readlane_b32 s6, v148, 48
	v_readlane_b32 s16, v148, 0
	v_readlane_b32 s17, v148, 32
	v_mov_b32_e32 v148, s0
	v_mov_b32_e32 v149, s6
	v_pk_add_f32 v[148:149], s[16:17], v[148:149]
	s_nop 0
	v_add_f32_e32 v148, v148, v149
	v_fmamk_f32 v148, v148, 0x3a800000, v219
	v_cmp_gt_f32_e32 vcc, s87, v148
	v_mul_f32_e32 v149, 0x4f800000, v148
	s_nop 0
	v_cndmask_b32_e32 v148, v148, v149, vcc
	v_sqrt_f32_e32 v149, v148
	s_nop 0
	v_add_u32_e32 v154, -1, v149
	v_fma_f32 v155, -v154, v149, v148
	v_cmp_ge_f32_e64 s[42:43], 0, v155
	v_add_u32_e32 v155, 1, v149
	s_nop 0
	v_cndmask_b32_e64 v154, v149, v154, s[42:43]
	v_fma_f32 v149, -v155, v149, v148
	v_cmp_lt_f32_e64 s[42:43], 0, v149
	s_nop 1
	v_cndmask_b32_e64 v149, v154, v155, s[42:43]
	v_mul_f32_e32 v154, 0x37800000, v149
	v_cndmask_b32_e32 v149, v149, v154, vcc
	v_cmp_class_f32_e32 vcc, v148, v213
	s_nop 1
	v_cndmask_b32_e32 v148, v149, v148, vcc
	v_div_scale_f32 v149, s[16:17], v148, v148, 1.0
	v_rcp_f32_e32 v154, v149
	s_lshl_b64 s[16:17], s[22:23], 2
	s_waitcnt lgkmcnt(0)
	s_add_u32 s20, s60, s16
	s_addc_u32 s21, s61, s17
	v_fma_f32 v155, -v149, v154, 1.0
	v_fmac_f32_e32 v154, v155, v154
	v_div_scale_f32 v155, vcc, 1.0, v148, 1.0
	v_mul_f32_e32 v156, v155, v154
	v_fma_f32 v157, -v149, v156, v155
	v_fmac_f32_e32 v156, v157, v154
	v_fma_f32 v149, -v149, v156, v155
	v_div_fmas_f32 v149, v149, v154, v156
	v_div_fixup_f32 v158, v149, v148, 1.0
	v_lshlrev_b64 v[148:149], 4, v[200:201]
	s_add_u32 s16, s62, s16
	v_lshl_add_u64 v[164:165], s[20:21], 0, v[148:149]
	s_addc_u32 s17, s63, s17
	v_lshl_add_u64 v[166:167], s[16:17], 0, v[148:149]
	v_pk_mul_f32 v[168:169], v[150:151], v[158:159] op_sel_hi:[1,0]
	global_load_dwordx4 v[148:151], v[164:165], off
	global_load_dwordx4 v[154:157], v[166:167], off
	s_ashr_i32 s55, s54, 31
	v_pk_mul_f32 v[152:153], v[152:153], v[158:159] op_sel_hi:[1,0]
	s_lshl_b64 s[16:17], s[54:55], 12
	v_lshl_add_u64 v[162:163], v[178:179], 0, s[16:17]
	s_andn2_b64 vcc, exec, s[50:51]
	s_waitcnt vmcnt(0)
	v_pk_fma_f32 v[152:153], v[150:151], v[152:153], v[156:157]
	v_pk_fma_f32 v[150:151], v[148:149], v[168:169], v[154:155]
	v_cndmask_b32_e64 v148, 0, 1, s[50:51]
	v_cmp_ne_u32_e64 s[42:43], 1, v148
	s_cbranch_vccnz .LBB0_507
	global_store_dwordx4 v[162:163], v[150:153], off nt sc1
; __device__ __forceinline__ void phase_rows(const Ctx& c, int l) {
;     ...
;             f32x4* orow = (f32x4*)(c.out + (size_t)m * DM) + lane;
; #pragma unroll
;             for (int j = 0; j < 4; ++j) { v[q][j] = v[q][j] * rstd * gp[64 * j] + bp[64 * j]; if (l == NLAYER) orow[64 * j] = v[q][j]; }
.LBB0_507:
	global_load_dwordx4 v[168:171], v[164:165], off offset:1024
	global_load_dwordx4 v[180:183], v[166:167], off offset:1024
	v_mov_b32_e32 v159, v158
	v_mov_b32_e32 v154, v158
	v_mov_b32_e32 v155, v158
	v_pk_mul_f32 v[148:149], v[160:161], v[154:155]
	v_pk_mul_f32 v[146:147], v[146:147], v[158:159]
	s_and_b64 vcc, exec, s[42:43]
	s_waitcnt vmcnt(0)
	v_pk_fma_f32 v[148:149], v[148:149], v[170:171], v[182:183]
	v_pk_fma_f32 v[146:147], v[146:147], v[168:169], v[180:181]
	s_cbranch_vccnz .LBB0_509
	global_store_dwordx4 v[162:163], v[146:149], off offset:1024 nt sc1
.LBB0_509:
	v_pk_mul_f32 v[160:161], v[144:145], v[154:155]
	v_pk_mul_f32 v[168:169], v[142:143], v[158:159]
	global_load_dwordx4 v[142:145], v[164:165], off offset:2048
	global_load_dwordx4 v[154:157], v[166:167], off offset:2048
	s_and_b64 vcc, exec, s[42:43]
	s_waitcnt vmcnt(0)
	v_pk_fma_f32 v[144:145], v[160:161], v[144:145], v[156:157]
	v_pk_fma_f32 v[142:143], v[168:169], v[142:143], v[154:155]
	s_cbranch_vccnz .LBB0_511
	global_store_dwordx4 v[162:163], v[142:145], off offset:2048 nt sc1
.LBB0_511:
	v_mov_b32_e32 v154, v158
	v_mov_b32_e32 v155, v158
	v_pk_mul_f32 v[160:161], v[140:141], v[154:155]
	v_pk_mul_f32 v[168:169], v[138:139], v[158:159]
	global_load_dwordx4 v[138:141], v[164:165], off offset:3072
	global_load_dwordx4 v[154:157], v[166:167], off offset:3072
	s_and_b64 vcc, exec, s[42:43]
	s_waitcnt vmcnt(0)
	v_pk_fma_f32 v[140:141], v[160:161], v[140:141], v[156:157]
	v_pk_fma_f32 v[138:139], v[168:169], v[138:139], v[154:155]
	s_cbranch_vccnz .LBB0_513
	global_store_dwordx4 v[162:163], v[138:141], off offset:3072 nt sc1
